# adds: s1 item issues its 12 staging loads back to back (counted waits at consumers); sample pool matvec loads batched 32 at a time instead of one per wait
# speedup vs baseline: 1.0271x; 1.0126x over previous
.LBB0_322:
	s_or_b64 exec, exec, s[4:5]
	s_waitcnt lgkmcnt(1)
	v_sub_f32_e32 v3, v3, v4
	v_mul_f32_e32 v3, 0x3fb8aa3b, v3
	v_exp_f32_e32 v3, v3
	v_and_b32_e32 v28, 0x7f, v18
	s_waitcnt lgkmcnt(0)
	s_barrier
	v_mul_f32_e32 v2, v2, v3
	ds_write_b32 v0, v2
	v_or_b32_e32 v0, s2, v28
	v_readlane_b32 s8, v253, 46
	v_ashrrev_i32_e32 v2, 4, v18
	v_lshlrev_b32_e32 v0, 11, v0
	v_readlane_b32 s9, v253, 47
	v_and_b32_e32 v6, -8, v2
	s_lshl_b32 s2, s7, 8
	v_lshl_add_u64 v[24:25], s[8:9], 0, v[0:1]
	v_ashrrev_i32_e32 v7, 31, v6
	v_lshl_add_u64 v[20:21], v[24:25], 0, s[2:3]
	v_lshlrev_b64 v[26:27], 1, v[6:7]
	v_lshl_add_u64 v[2:3], v[20:21], 0, v[26:27]
	s_waitcnt lgkmcnt(0)
	s_barrier
	s_lshl_b32 s98, s7, 9
	s_mov_b32 s99, 0
	v_lshl_add_u64 v[144:145], v[24:25], 0, s[98:99]
	v_lshl_add_u64 v[144:145], v[144:145], 0, v[26:27]
	global_load_dwordx4 v[96:99], v[2:3], off offset:1024
	global_load_dwordx4 v[100:103], v[2:3], off offset:1088
	global_load_dwordx4 v[104:107], v[2:3], off offset:1152
	global_load_dwordx4 v[108:111], v[2:3], off offset:1216
	global_load_dwordx4 v[112:115], v[144:145], off
	global_load_dwordx4 v[116:119], v[144:145], off offset:64
	global_load_dwordx4 v[120:123], v[144:145], off offset:128
	global_load_dwordx4 v[124:127], v[144:145], off offset:192
	global_load_dwordx4 v[128:131], v[144:145], off offset:256
	global_load_dwordx4 v[132:135], v[144:145], off offset:320
	global_load_dwordx4 v[136:139], v[144:145], off offset:384
	global_load_dwordx4 v[140:143], v[144:145], off offset:448
	v_lshl_add_u32 v0, v28, 1, 0
	s_movk_i32 s8, 0x110
	v_mad_u64_u32 v[16:17], s[4:5], v6, s8, v[0:1]
	v_add_u32_e32 v29, 0x200, v18
	v_add_u32_e32 v17, 0x400, v18
	s_lshl_b32 s2, s7, 9
	v_and_b32_e32 v19, 15, v18
	v_readlane_b32 s10, v253, 48
	v_readlane_b32 s11, v253, 49
	s_waitcnt vmcnt(11)
	v_mov_b64_e32 v[2:3], v[96:97]
	v_mov_b64_e32 v[4:5], v[98:99]
	ds_write_b16 v16, v2
	ds_write_b16_d16_hi v16, v2 offset:272
	ds_write_b16 v16, v3 offset:544
	ds_write_b16_d16_hi v16, v3 offset:816
	ds_write_b16 v16, v4 offset:1088
	ds_write_b16_d16_hi v16, v4 offset:1360
	ds_write_b16 v16, v5 offset:1632
	ds_write_b16_d16_hi v16, v5 offset:1904
	v_ashrrev_i32_e32 v2, 4, v29
	v_and_b32_e32 v6, -8, v2
	v_ashrrev_i32_e32 v7, 31, v6
	v_lshlrev_b64 v[14:15], 1, v[6:7]
	v_lshl_add_u64 v[2:3], v[20:21], 0, v[14:15]
	v_mad_u64_u32 v[12:13], s[4:5], v6, s8, v[0:1]
	v_add_u32_e32 v13, 0x600, v18
	s_waitcnt vmcnt(10)
	v_mov_b64_e32 v[2:3], v[100:101]
	v_mov_b64_e32 v[4:5], v[102:103]
	ds_write_b16 v12, v2
	ds_write_b16_d16_hi v12, v2 offset:272
	ds_write_b16 v12, v3 offset:544
	ds_write_b16_d16_hi v12, v3 offset:816
	ds_write_b16 v12, v4 offset:1088
	ds_write_b16_d16_hi v12, v4 offset:1360
	ds_write_b16 v12, v5 offset:1632
	ds_write_b16_d16_hi v12, v5 offset:1904
	v_ashrrev_i32_e32 v2, 4, v17
	v_and_b32_e32 v6, -8, v2
	v_ashrrev_i32_e32 v7, 31, v6
	v_lshlrev_b64 v[10:11], 1, v[6:7]
	v_lshl_add_u64 v[2:3], v[20:21], 0, v[10:11]
	v_mad_u64_u32 v[8:9], s[4:5], v6, s8, v[0:1]
	s_waitcnt vmcnt(9)
	v_mov_b64_e32 v[2:3], v[104:105]
	v_mov_b64_e32 v[4:5], v[106:107]
	ds_write_b16 v8, v2
	ds_write_b16_d16_hi v8, v2 offset:272
	ds_write_b16 v8, v3 offset:544
	ds_write_b16_d16_hi v8, v3 offset:816
	ds_write_b16 v8, v4 offset:1088
	ds_write_b16_d16_hi v8, v4 offset:1360
	ds_write_b16 v8, v5 offset:1632
	ds_write_b16_d16_hi v8, v5 offset:1904
	v_ashrrev_i32_e32 v2, 4, v13
	v_and_b32_e32 v2, -8, v2
	v_ashrrev_i32_e32 v3, 31, v2
	v_lshlrev_b64 v[6:7], 1, v[2:3]
	v_lshl_add_u64 v[4:5], v[20:21], 0, v[6:7]
	v_mad_u64_u32 v[4:5], s[4:5], v2, s8, v[0:1]
	v_lshl_add_u64 v[2:3], v[24:25], 0, s[2:3]
	v_ashrrev_i32_e32 v5, 3, v18
	s_add_i32 s2, 0, 0x1a000
	v_lshlrev_b32_e32 v5, 2, v5
	v_lshl_add_u32 v9, v28, 2, s2
	v_and_b32_e32 v5, 0xfffffe00, v5
	v_add_u32_e32 v5, v9, v5
	v_lshl_add_u64 v[14:15], v[2:3], 0, v[14:15]
	v_lshl_add_u64 v[10:11], v[2:3], 0, v[10:11]
	v_lshl_add_u64 v[6:7], v[2:3], 0, v[6:7]
	s_mov_b32 s2, 0xfffffe0
	s_waitcnt vmcnt(8)
	v_mov_b64_e32 v[20:21], v[108:109]
	v_mov_b64_e32 v[22:23], v[110:111]
	ds_write_b16 v4, v20
	ds_write_b16_d16_hi v4, v20 offset:272
	ds_write_b16 v4, v21 offset:544
	ds_write_b16_d16_hi v4, v21 offset:816
	ds_write_b16 v4, v22 offset:1088
	ds_write_b16_d16_hi v4, v22 offset:1360
	ds_write_b16 v4, v23 offset:1632
	ds_write_b16_d16_hi v4, v23 offset:1904
	v_lshl_add_u64 v[20:21], v[2:3], 0, v[26:27]
	ds_read_b32 v5, v5
	s_waitcnt vmcnt(7)
	v_mov_b64_e32 v[20:21], v[112:113]
	v_mov_b64_e32 v[22:23], v[114:115]
	v_lshlrev_b32_e32 v24, 16, v20
	v_and_b32_e32 v20, 0xffff0000, v20
	s_waitcnt lgkmcnt(0)
	v_mul_f32_e32 v20, v5, v20
	v_cvt_pk_bf16_f32 v20, v20, v1
	ds_write_b16 v16, v20 offset:35088
	v_lshlrev_b32_e32 v20, 16, v21
	v_mul_f32_e32 v20, v5, v20
	v_cvt_pk_bf16_f32 v20, v20, v1
	ds_write_b16 v16, v20 offset:35360
	v_and_b32_e32 v20, 0xffff0000, v21
	v_mul_f32_e32 v20, v5, v20
	v_cvt_pk_bf16_f32 v20, v20, v1
	ds_write_b16 v16, v20 offset:35632
	v_lshlrev_b32_e32 v20, 16, v22
	v_mul_f32_e32 v20, v5, v20
	v_cvt_pk_bf16_f32 v20, v20, v1
	ds_write_b16 v16, v20 offset:35904
	v_and_b32_e32 v20, 0xffff0000, v22
	v_mul_f32_e32 v20, v5, v20
	v_cvt_pk_bf16_f32 v20, v20, v1
	ds_write_b16 v16, v20 offset:36176
	v_lshlrev_b32_e32 v20, 16, v23
	v_mul_f32_e32 v20, v5, v20
	v_cvt_pk_bf16_f32 v20, v20, v1
	ds_write_b16 v16, v20 offset:36448
	v_and_b32_e32 v20, 0xffff0000, v23
	v_mul_f32_e32 v24, v5, v24
	v_mul_f32_e32 v5, v5, v20
	v_cvt_pk_bf16_f32 v5, v5, v1
	ds_write_b16 v16, v5 offset:36720
	v_ashrrev_i32_e32 v5, 3, v29
	v_lshlrev_b32_e32 v5, 2, v5
	v_and_b32_e32 v5, 0xfffffe00, v5
	v_add_u32_e32 v5, v9, v5
	ds_read_b32 v5, v5
	v_cvt_pk_bf16_f32 v24, v24, v1
	ds_write_b16 v16, v24 offset:34816
	s_waitcnt vmcnt(6)
	v_mov_b64_e32 v[20:21], v[116:117]
	v_mov_b64_e32 v[22:23], v[118:119]
	v_lshlrev_b32_e32 v14, 16, v20
	s_waitcnt lgkmcnt(1)
	v_mul_f32_e32 v14, v5, v14
	v_cvt_pk_bf16_f32 v14, v14, v1
	ds_write_b16 v12, v14 offset:34816
	v_and_b32_e32 v14, 0xffff0000, v20
	v_mul_f32_e32 v14, v5, v14
	v_cvt_pk_bf16_f32 v14, v14, v1
	ds_write_b16 v12, v14 offset:35088
	v_lshlrev_b32_e32 v14, 16, v21
	v_mul_f32_e32 v14, v5, v14
	v_cvt_pk_bf16_f32 v14, v14, v1
	ds_write_b16 v12, v14 offset:35360
	v_and_b32_e32 v14, 0xffff0000, v21
	v_mul_f32_e32 v14, v5, v14
	v_cvt_pk_bf16_f32 v14, v14, v1
	ds_write_b16 v12, v14 offset:35632
	v_lshlrev_b32_e32 v14, 16, v22
	v_mul_f32_e32 v14, v5, v14
	v_cvt_pk_bf16_f32 v14, v14, v1
	ds_write_b16 v12, v14 offset:35904
	v_and_b32_e32 v14, 0xffff0000, v22
	v_mul_f32_e32 v14, v5, v14
	v_cvt_pk_bf16_f32 v14, v14, v1
	ds_write_b16 v12, v14 offset:36176
	v_lshlrev_b32_e32 v14, 16, v23
	v_mul_f32_e32 v14, v5, v14
	v_cvt_pk_bf16_f32 v14, v14, v1
	ds_write_b16 v12, v14 offset:36448
	v_and_b32_e32 v14, 0xffff0000, v23
	v_mul_f32_e32 v5, v5, v14
	v_cvt_pk_bf16_f32 v5, v5, v1
	ds_write_b16 v12, v5 offset:36720
	v_ashrrev_i32_e32 v5, 3, v17
	v_lshlrev_b32_e32 v5, 2, v5
	v_and_b32_e32 v5, 0xfffffe00, v5
	v_add_u32_e32 v5, v9, v5
	ds_read_b32 v5, v5
	v_ashrrev_i32_e32 v12, 1, v18
	s_waitcnt vmcnt(5)
	v_mov_b64_e32 v[20:21], v[120:121]
	v_mov_b64_e32 v[22:23], v[122:123]
	v_lshlrev_b32_e32 v10, 16, v20
	s_waitcnt lgkmcnt(0)
	v_mul_f32_e32 v10, v5, v10
	v_cvt_pk_bf16_f32 v10, v10, v1
	ds_write_b16 v8, v10 offset:34816
	v_and_b32_e32 v10, 0xffff0000, v20
	v_mul_f32_e32 v10, v5, v10
	v_cvt_pk_bf16_f32 v10, v10, v1
	ds_write_b16 v8, v10 offset:35088
	v_lshlrev_b32_e32 v10, 16, v21
	v_mul_f32_e32 v10, v5, v10
	v_cvt_pk_bf16_f32 v10, v10, v1
	ds_write_b16 v8, v10 offset:35360
	v_and_b32_e32 v10, 0xffff0000, v21
	v_mul_f32_e32 v10, v5, v10
	v_cvt_pk_bf16_f32 v10, v10, v1
	ds_write_b16 v8, v10 offset:35632
	v_lshlrev_b32_e32 v10, 16, v22
	v_mul_f32_e32 v10, v5, v10
	v_cvt_pk_bf16_f32 v10, v10, v1
	ds_write_b16 v8, v10 offset:35904
	v_and_b32_e32 v10, 0xffff0000, v22
	v_mul_f32_e32 v10, v5, v10
	v_cvt_pk_bf16_f32 v10, v10, v1
	ds_write_b16 v8, v10 offset:36176
	v_lshlrev_b32_e32 v10, 16, v23
	v_mul_f32_e32 v10, v5, v10
	v_cvt_pk_bf16_f32 v10, v10, v1
	ds_write_b16 v8, v10 offset:36448
	v_and_b32_e32 v10, 0xffff0000, v23
	v_mul_f32_e32 v5, v5, v10
	v_cvt_pk_bf16_f32 v5, v5, v1
	ds_write_b16 v8, v5 offset:36720
	v_ashrrev_i32_e32 v5, 3, v13
	v_lshlrev_b32_e32 v5, 2, v5
	v_and_b32_e32 v5, 0xfffffe00, v5
	v_add_u32_e32 v5, v9, v5
	ds_read_b32 v5, v5
	s_waitcnt vmcnt(4)
	v_mov_b64_e32 v[14:15], v[124:125]
	v_mov_b64_e32 v[16:17], v[126:127]
	v_lshlrev_b32_e32 v6, 16, v14
	v_add_u32_e32 v8, 0x800, v18
	s_waitcnt lgkmcnt(0)
	v_mul_f32_e32 v6, v5, v6
	v_cvt_pk_bf16_f32 v6, v6, v1
	ds_write_b16 v4, v6 offset:34816
	v_and_b32_e32 v6, 0xffff0000, v14
	v_mul_f32_e32 v6, v5, v6
	v_cvt_pk_bf16_f32 v6, v6, v1
	ds_write_b16 v4, v6 offset:35088
	v_lshlrev_b32_e32 v6, 16, v15
	v_mul_f32_e32 v6, v5, v6
	v_cvt_pk_bf16_f32 v6, v6, v1
	ds_write_b16 v4, v6 offset:35360
	v_and_b32_e32 v6, 0xffff0000, v15
	v_mul_f32_e32 v6, v5, v6
	v_cvt_pk_bf16_f32 v6, v6, v1
	ds_write_b16 v4, v6 offset:35632
	v_lshlrev_b32_e32 v6, 16, v16
	v_mul_f32_e32 v6, v5, v6
	v_cvt_pk_bf16_f32 v6, v6, v1
	ds_write_b16 v4, v6 offset:35904
	v_and_b32_e32 v6, 0xffff0000, v16
	v_mul_f32_e32 v6, v5, v6
	v_cvt_pk_bf16_f32 v6, v6, v1
	ds_write_b16 v4, v6 offset:36176
	v_lshlrev_b32_e32 v6, 16, v17
	v_mul_f32_e32 v6, v5, v6
	v_cvt_pk_bf16_f32 v6, v6, v1
	ds_write_b16 v4, v6 offset:36448
	v_and_b32_e32 v6, 0xffff0000, v17
	v_mul_f32_e32 v5, v5, v6
	v_cvt_pk_bf16_f32 v5, v5, v1
	ds_write_b16 v4, v5 offset:36720
	v_ashrrev_i32_e32 v4, 4, v8
	v_and_b32_e32 v10, -8, v4
	v_ashrrev_i32_e32 v11, 31, v10
	v_lshl_add_u64 v[4:5], v[10:11], 1, v[2:3]
	v_ashrrev_i32_e32 v8, 3, v8
	v_lshlrev_b32_e32 v8, 2, v8
	v_and_b32_e32 v8, 0xfffffe00, v8
	v_add_u32_e32 v8, v9, v8
	ds_read_b32 v8, v8
	v_mad_u64_u32 v[10:11], s[4:5], v10, s8, v[0:1]
	s_waitcnt vmcnt(3)
	v_mov_b64_e32 v[4:5], v[128:129]
	v_mov_b64_e32 v[6:7], v[130:131]
	v_lshlrev_b32_e32 v11, 16, v4
	v_and_b32_e32 v4, 0xffff0000, v4
	s_waitcnt lgkmcnt(0)
	v_mul_f32_e32 v4, v8, v4
	v_cvt_pk_bf16_f32 v4, v4, v1
	ds_write_b16 v10, v4 offset:35088
	v_lshlrev_b32_e32 v4, 16, v5
	v_mul_f32_e32 v4, v8, v4
	v_cvt_pk_bf16_f32 v4, v4, v1
	ds_write_b16 v10, v4 offset:35360
	v_and_b32_e32 v4, 0xffff0000, v5
	v_mul_f32_e32 v4, v8, v4
	v_cvt_pk_bf16_f32 v4, v4, v1
	ds_write_b16 v10, v4 offset:35632
	v_lshlrev_b32_e32 v4, 16, v6
	v_mul_f32_e32 v4, v8, v4
	v_cvt_pk_bf16_f32 v4, v4, v1
	ds_write_b16 v10, v4 offset:35904
	v_and_b32_e32 v4, 0xffff0000, v6
	v_mul_f32_e32 v4, v8, v4
	v_cvt_pk_bf16_f32 v4, v4, v1
	ds_write_b16 v10, v4 offset:36176
	v_lshlrev_b32_e32 v4, 16, v7
	v_mul_f32_e32 v4, v8, v4
	v_cvt_pk_bf16_f32 v4, v4, v1
	ds_write_b16 v10, v4 offset:36448
	v_and_b32_e32 v4, 0xffff0000, v7
	v_mul_f32_e32 v4, v8, v4
	v_mul_f32_e32 v11, v8, v11
	v_cvt_pk_bf16_f32 v4, v4, v1
	v_add_u32_e32 v8, 0xa00, v18
	ds_write_b16 v10, v4 offset:36720
	v_ashrrev_i32_e32 v4, 4, v8
	v_cvt_pk_bf16_f32 v11, v11, v1
	ds_write_b16 v10, v11 offset:34816
	v_and_b32_e32 v10, -8, v4
	v_ashrrev_i32_e32 v11, 31, v10
	v_lshl_add_u64 v[4:5], v[10:11], 1, v[2:3]
	v_ashrrev_i32_e32 v8, 3, v8
	v_lshlrev_b32_e32 v8, 2, v8
	v_and_b32_e32 v8, 0xfffffe00, v8
	v_add_u32_e32 v8, v9, v8
	ds_read_b32 v8, v8
	v_mad_u64_u32 v[10:11], s[4:5], v10, s8, v[0:1]
	s_waitcnt vmcnt(2)
	v_mov_b64_e32 v[4:5], v[132:133]
	v_mov_b64_e32 v[6:7], v[134:135]
	v_lshlrev_b32_e32 v11, 16, v4
	v_and_b32_e32 v4, 0xffff0000, v4
	s_waitcnt lgkmcnt(0)
	v_mul_f32_e32 v4, v8, v4
	v_cvt_pk_bf16_f32 v4, v4, v1
	ds_write_b16 v10, v4 offset:35088
	v_lshlrev_b32_e32 v4, 16, v5
	v_mul_f32_e32 v4, v8, v4
	v_cvt_pk_bf16_f32 v4, v4, v1
	ds_write_b16 v10, v4 offset:35360
	v_and_b32_e32 v4, 0xffff0000, v5
	v_mul_f32_e32 v4, v8, v4
	v_cvt_pk_bf16_f32 v4, v4, v1
	ds_write_b16 v10, v4 offset:35632
	v_lshlrev_b32_e32 v4, 16, v6
	v_mul_f32_e32 v4, v8, v4
	v_cvt_pk_bf16_f32 v4, v4, v1
	ds_write_b16 v10, v4 offset:35904
	v_and_b32_e32 v4, 0xffff0000, v6
	v_mul_f32_e32 v4, v8, v4
	v_cvt_pk_bf16_f32 v4, v4, v1
	ds_write_b16 v10, v4 offset:36176
	v_lshlrev_b32_e32 v4, 16, v7
	v_mul_f32_e32 v4, v8, v4
	v_cvt_pk_bf16_f32 v4, v4, v1
	ds_write_b16 v10, v4 offset:36448
	v_and_b32_e32 v4, 0xffff0000, v7
	v_mul_f32_e32 v4, v8, v4
	v_mul_f32_e32 v11, v8, v11
	v_cvt_pk_bf16_f32 v4, v4, v1
	v_add_u32_e32 v8, 0xc00, v18
	ds_write_b16 v10, v4 offset:36720
	v_ashrrev_i32_e32 v4, 4, v8
	v_cvt_pk_bf16_f32 v11, v11, v1
	ds_write_b16 v10, v11 offset:34816
	v_and_b32_e32 v10, -8, v4
	v_ashrrev_i32_e32 v11, 31, v10
	v_lshl_add_u64 v[4:5], v[10:11], 1, v[2:3]
	v_ashrrev_i32_e32 v8, 3, v8
	v_lshlrev_b32_e32 v8, 2, v8
	v_and_b32_e32 v8, 0xfffffe00, v8
	v_add_u32_e32 v8, v9, v8
	ds_read_b32 v8, v8
	v_mad_u64_u32 v[10:11], s[4:5], v10, s8, v[0:1]
	s_waitcnt vmcnt(1)
	v_mov_b64_e32 v[4:5], v[136:137]
	v_mov_b64_e32 v[6:7], v[138:139]
	v_lshlrev_b32_e32 v11, 16, v4
	v_and_b32_e32 v4, 0xffff0000, v4
	s_waitcnt lgkmcnt(0)
	v_mul_f32_e32 v4, v8, v4
	v_cvt_pk_bf16_f32 v4, v4, v1
	ds_write_b16 v10, v4 offset:35088
	v_lshlrev_b32_e32 v4, 16, v5
	v_mul_f32_e32 v4, v8, v4
	v_cvt_pk_bf16_f32 v4, v4, v1
	ds_write_b16 v10, v4 offset:35360
	v_and_b32_e32 v4, 0xffff0000, v5
	v_mul_f32_e32 v4, v8, v4
	v_cvt_pk_bf16_f32 v4, v4, v1
	ds_write_b16 v10, v4 offset:35632
	v_lshlrev_b32_e32 v4, 16, v6
	v_mul_f32_e32 v4, v8, v4
	v_cvt_pk_bf16_f32 v4, v4, v1
	ds_write_b16 v10, v4 offset:35904
	v_and_b32_e32 v4, 0xffff0000, v6
	v_mul_f32_e32 v4, v8, v4
	v_cvt_pk_bf16_f32 v4, v4, v1
	ds_write_b16 v10, v4 offset:36176
	v_lshlrev_b32_e32 v4, 16, v7
	v_mul_f32_e32 v4, v8, v4
	v_cvt_pk_bf16_f32 v4, v4, v1
	ds_write_b16 v10, v4 offset:36448
	v_and_b32_e32 v4, 0xffff0000, v7
	v_mul_f32_e32 v4, v8, v4
	v_mul_f32_e32 v11, v8, v11
	v_cvt_pk_bf16_f32 v4, v4, v1
	v_add_u32_e32 v8, 0xe00, v18
	ds_write_b16 v10, v4 offset:36720
	v_ashrrev_i32_e32 v4, 4, v8
	v_and_b32_e32 v6, -8, v4
	v_ashrrev_i32_e32 v7, 31, v6
	v_lshl_add_u64 v[2:3], v[6:7], 1, v[2:3]
	v_ashrrev_i32_e32 v7, 3, v8
	v_lshlrev_b32_e32 v7, 2, v7
	v_and_b32_e32 v7, 0xfffffe00, v7
	v_add_u32_e32 v7, v9, v7
	ds_read_b32 v8, v7
	v_mad_u64_u32 v[6:7], s[4:5], v6, s8, v[0:1]
	v_cvt_pk_bf16_f32 v11, v11, v1
	ds_write_b16 v10, v11 offset:34816
	s_waitcnt vmcnt(0)
	v_mov_b64_e32 v[2:3], v[140:141]
	v_mov_b64_e32 v[4:5], v[142:143]
	v_lshlrev_b32_e32 v0, 16, v2
	s_waitcnt lgkmcnt(1)
	v_mul_f32_e32 v0, v8, v0
	v_cvt_pk_bf16_f32 v0, v0, v1
	ds_write_b16 v6, v0 offset:34816
	v_and_b32_e32 v0, 0xffff0000, v2
	v_mul_f32_e32 v0, v8, v0
	v_cvt_pk_bf16_f32 v0, v0, v1
	ds_write_b16 v6, v0 offset:35088
	v_lshlrev_b32_e32 v0, 16, v3
	v_mul_f32_e32 v0, v8, v0
	v_cvt_pk_bf16_f32 v0, v0, v1
	ds_write_b16 v6, v0 offset:35360
	v_and_b32_e32 v0, 0xffff0000, v3
	v_mul_f32_e32 v0, v8, v0
	v_cvt_pk_bf16_f32 v0, v0, v1
	ds_write_b16 v6, v0 offset:35632
	v_lshlrev_b32_e32 v0, 16, v4
	v_mul_f32_e32 v0, v8, v0
	v_cvt_pk_bf16_f32 v0, v0, v1
	ds_write_b16 v6, v0 offset:35904
	v_and_b32_e32 v0, 0xffff0000, v4
	v_mul_f32_e32 v0, v8, v0
	v_cvt_pk_bf16_f32 v0, v0, v1
	ds_write_b16 v6, v0 offset:36176
	v_lshlrev_b32_e32 v0, 16, v5
	v_mul_f32_e32 v0, v8, v0
	v_cvt_pk_bf16_f32 v0, v0, v1
	ds_write_b16 v6, v0 offset:36448
	v_and_b32_e32 v0, 0xffff0000, v5
	v_mul_f32_e32 v0, v8, v0
	v_cvt_pk_bf16_f32 v0, v0, v1
	ds_write_b16 v6, v0 offset:36720
	v_and_b32_e32 v0, 48, v18
	v_and_or_b32 v2, v12, s2, v19
	v_add_u32_e32 v14, 0, v0
	v_mad_u64_u32 v[10:11], s[4:5], v2, s8, v[14:15]
	v_mad_u32_u24 v11, v19, s8, v14
	s_waitcnt lgkmcnt(0)
	s_barrier
	ds_read_b128 v[2:5], v10 offset:34816
	ds_read_b128 v[6:9], v10 offset:39168
	ds_read_b128 v[14:17], v11
	ds_read_b128 v[24:27], v11 offset:4352
	ds_read_b128 v[32:35], v11 offset:8704
	ds_read_b128 v[40:43], v11 offset:13056
	ds_read_b128 v[48:51], v11 offset:17408
	ds_read_b128 v[56:59], v11 offset:21760
	ds_read_b128 v[64:67], v11 offset:26112
	ds_read_b128 v[72:75], v11 offset:30464
	s_waitcnt lgkmcnt(7)
	v_mfma_f32_16x16x32_bf16 v[20:23], v[14:17], v[2:5], 0
	v_readlane_b32 s4, v254, 9
	v_readlane_b32 s5, v254, 10
	v_mfma_f32_16x16x32_bf16 v[14:17], v[14:17], v[6:9], 0
	s_waitcnt lgkmcnt(6)
	v_mfma_f32_16x16x32_bf16 v[28:31], v[24:27], v[2:5], 0
	v_mfma_f32_16x16x32_bf16 v[24:27], v[24:27], v[6:9], 0
	s_waitcnt lgkmcnt(5)
	v_mfma_f32_16x16x32_bf16 v[36:39], v[32:35], v[2:5], 0
	v_mfma_f32_16x16x32_bf16 v[32:35], v[32:35], v[6:9], 0
	s_waitcnt lgkmcnt(4)
	v_mfma_f32_16x16x32_bf16 v[44:47], v[40:43], v[2:5], 0
	v_mfma_f32_16x16x32_bf16 v[40:43], v[40:43], v[6:9], 0
	s_waitcnt lgkmcnt(3)
	v_mfma_f32_16x16x32_bf16 v[52:55], v[48:51], v[2:5], 0
	v_mfma_f32_16x16x32_bf16 v[48:51], v[48:51], v[6:9], 0
	s_waitcnt lgkmcnt(2)
	v_mfma_f32_16x16x32_bf16 v[60:63], v[56:59], v[2:5], 0
	v_mfma_f32_16x16x32_bf16 v[56:59], v[56:59], v[6:9], 0
	s_waitcnt lgkmcnt(1)
	v_mfma_f32_16x16x32_bf16 v[68:71], v[64:67], v[2:5], 0
	v_mfma_f32_16x16x32_bf16 v[64:67], v[64:67], v[6:9], 0
	s_waitcnt lgkmcnt(0)
	v_mfma_f32_16x16x32_bf16 v[2:5], v[72:75], v[2:5], 0
	v_mfma_f32_16x16x32_bf16 v[6:9], v[72:75], v[6:9], 0
	ds_read_b128 v[72:75], v10 offset:34880
	ds_read_b128 v[76:79], v10 offset:39232
	ds_read_b128 v[80:83], v11 offset:64
	s_waitcnt lgkmcnt(0)
	v_mfma_f32_16x16x32_bf16 v[20:23], v[80:83], v[72:75], v[20:23]
	v_mfma_f32_16x16x32_bf16 v[14:17], v[80:83], v[76:79], v[14:17]
	ds_read_b128 v[80:83], v11 offset:4416
	s_waitcnt lgkmcnt(0)
	v_mfma_f32_16x16x32_bf16 v[28:31], v[80:83], v[72:75], v[28:31]
	v_mfma_f32_16x16x32_bf16 v[24:27], v[80:83], v[76:79], v[24:27]
	ds_read_b128 v[80:83], v11 offset:8768
	s_waitcnt lgkmcnt(0)
	v_mfma_f32_16x16x32_bf16 v[36:39], v[80:83], v[72:75], v[36:39]
	v_mfma_f32_16x16x32_bf16 v[32:35], v[80:83], v[76:79], v[32:35]
	ds_read_b128 v[80:83], v11 offset:13120
	s_waitcnt lgkmcnt(0)
	v_mfma_f32_16x16x32_bf16 v[44:47], v[80:83], v[72:75], v[44:47]
	v_mfma_f32_16x16x32_bf16 v[40:43], v[80:83], v[76:79], v[40:43]
	ds_read_b128 v[80:83], v11 offset:17472
	s_waitcnt lgkmcnt(0)
	v_mfma_f32_16x16x32_bf16 v[52:55], v[80:83], v[72:75], v[52:55]
	v_mfma_f32_16x16x32_bf16 v[48:51], v[80:83], v[76:79], v[48:51]
	ds_read_b128 v[80:83], v11 offset:21824
	s_waitcnt lgkmcnt(0)
	v_mfma_f32_16x16x32_bf16 v[60:63], v[80:83], v[72:75], v[60:63]
	v_mfma_f32_16x16x32_bf16 v[56:59], v[80:83], v[76:79], v[56:59]
	ds_read_b128 v[80:83], v11 offset:26176
	s_waitcnt lgkmcnt(0)
	v_mfma_f32_16x16x32_bf16 v[68:71], v[80:83], v[72:75], v[68:71]
	v_mfma_f32_16x16x32_bf16 v[64:67], v[80:83], v[76:79], v[64:67]
	ds_read_b128 v[80:83], v11 offset:30528
	s_waitcnt lgkmcnt(0)
	v_mfma_f32_16x16x32_bf16 v[2:5], v[80:83], v[72:75], v[2:5]
	v_mfma_f32_16x16x32_bf16 v[6:9], v[80:83], v[76:79], v[6:9]
	ds_read_b128 v[72:75], v10 offset:34944
	ds_read_b128 v[76:79], v10 offset:39296
	ds_read_b128 v[80:83], v11 offset:128
	s_waitcnt lgkmcnt(0)
	v_mfma_f32_16x16x32_bf16 v[20:23], v[80:83], v[72:75], v[20:23]
	v_mfma_f32_16x16x32_bf16 v[14:17], v[80:83], v[76:79], v[14:17]
	ds_read_b128 v[80:83], v11 offset:4480
	s_waitcnt lgkmcnt(0)
	v_mfma_f32_16x16x32_bf16 v[28:31], v[80:83], v[72:75], v[28:31]
	v_mfma_f32_16x16x32_bf16 v[24:27], v[80:83], v[76:79], v[24:27]
	ds_read_b128 v[80:83], v11 offset:8832
	s_waitcnt lgkmcnt(0)
	v_mfma_f32_16x16x32_bf16 v[36:39], v[80:83], v[72:75], v[36:39]
	v_mfma_f32_16x16x32_bf16 v[32:35], v[80:83], v[76:79], v[32:35]
	ds_read_b128 v[80:83], v11 offset:13184
	s_waitcnt lgkmcnt(0)
	v_mfma_f32_16x16x32_bf16 v[44:47], v[80:83], v[72:75], v[44:47]
	v_mfma_f32_16x16x32_bf16 v[40:43], v[80:83], v[76:79], v[40:43]
	ds_read_b128 v[80:83], v11 offset:17536
	s_waitcnt lgkmcnt(0)
	v_mfma_f32_16x16x32_bf16 v[52:55], v[80:83], v[72:75], v[52:55]
	v_mfma_f32_16x16x32_bf16 v[48:51], v[80:83], v[76:79], v[48:51]
	ds_read_b128 v[80:83], v11 offset:21888
	s_waitcnt lgkmcnt(0)
	v_mfma_f32_16x16x32_bf16 v[60:63], v[80:83], v[72:75], v[60:63]
	v_mfma_f32_16x16x32_bf16 v[56:59], v[80:83], v[76:79], v[56:59]
	ds_read_b128 v[80:83], v11 offset:26240
	s_waitcnt lgkmcnt(0)
	v_mfma_f32_16x16x32_bf16 v[68:71], v[80:83], v[72:75], v[68:71]
	v_mfma_f32_16x16x32_bf16 v[64:67], v[80:83], v[76:79], v[64:67]
	ds_read_b128 v[80:83], v11 offset:30592
	s_waitcnt lgkmcnt(0)
	v_mfma_f32_16x16x32_bf16 v[2:5], v[80:83], v[72:75], v[2:5]
	v_mfma_f32_16x16x32_bf16 v[6:9], v[80:83], v[76:79], v[6:9]
	ds_read_b128 v[72:75], v10 offset:35008
	ds_read_b128 v[76:79], v10 offset:39360
	ds_read_b128 v[80:83], v11 offset:192
	v_ashrrev_i32_e32 v10, 7, v18
	v_add_u32_e32 v10, s6, v10
	s_waitcnt lgkmcnt(0)
	v_mfma_f32_16x16x32_bf16 v[20:23], v[80:83], v[72:75], v[20:23]
	v_and_or_b32 v18, v12, 32, v19
	v_lshl_add_u64 v[12:13], s[4:5], 0, v[0:1]
	v_lshlrev_b32_e32 v0, 9, v18
	v_mfma_f32_16x16x32_bf16 v[14:17], v[80:83], v[76:79], v[14:17]
	ds_read_b128 v[80:83], v11 offset:4544
	s_mov_b64 s[4:5], 0
	s_waitcnt lgkmcnt(0)
	v_mfma_f32_16x16x32_bf16 v[28:31], v[80:83], v[72:75], v[28:31]
	v_mfma_f32_16x16x32_bf16 v[24:27], v[80:83], v[76:79], v[24:27]
	ds_read_b128 v[80:83], v11 offset:8896
	s_waitcnt lgkmcnt(0)
	v_mfma_f32_16x16x32_bf16 v[36:39], v[80:83], v[72:75], v[36:39]
	v_mfma_f32_16x16x32_bf16 v[32:35], v[80:83], v[76:79], v[32:35]
	ds_read_b128 v[80:83], v11 offset:13248
	s_waitcnt lgkmcnt(0)
	v_mfma_f32_16x16x32_bf16 v[44:47], v[80:83], v[72:75], v[44:47]
	v_mfma_f32_16x16x32_bf16 v[40:43], v[80:83], v[76:79], v[40:43]
	ds_read_b128 v[80:83], v11 offset:17600
	s_waitcnt lgkmcnt(0)
	v_mfma_f32_16x16x32_bf16 v[52:55], v[80:83], v[72:75], v[52:55]
	v_mfma_f32_16x16x32_bf16 v[48:51], v[80:83], v[76:79], v[48:51]
	ds_read_b128 v[80:83], v11 offset:21952
	s_waitcnt lgkmcnt(0)
	v_mfma_f32_16x16x32_bf16 v[60:63], v[80:83], v[72:75], v[60:63]
	v_mfma_f32_16x16x32_bf16 v[56:59], v[80:83], v[76:79], v[56:59]
	ds_read_b128 v[80:83], v11 offset:26304
	s_waitcnt lgkmcnt(0)
	v_mfma_f32_16x16x32_bf16 v[68:71], v[80:83], v[72:75], v[68:71]
	v_mfma_f32_16x16x32_bf16 v[64:67], v[80:83], v[76:79], v[64:67]
	ds_read_b128 v[80:83], v11 offset:30656
	v_ashrrev_i32_e32 v11, 31, v10
	v_lshlrev_b64 v[10:11], 15, v[10:11]
	v_lshl_add_u64 v[10:11], v[12:13], 0, v[10:11]
	s_waitcnt lgkmcnt(0)
	v_mfma_f32_16x16x32_bf16 v[2:5], v[80:83], v[72:75], v[2:5]
	v_lshl_add_u64 v[10:11], v[10:11], 0, v[0:1]
	global_store_dwordx4 v[10:11], v[20:23], off
	global_store_dwordx4 v[10:11], v[28:31], off offset:64
	global_store_dwordx4 v[10:11], v[36:39], off offset:128
	global_store_dwordx4 v[10:11], v[44:47], off offset:192
	global_store_dwordx4 v[10:11], v[52:55], off offset:256
	global_store_dwordx4 v[10:11], v[60:63], off offset:320
	global_store_dwordx4 v[10:11], v[68:71], off offset:384
	global_store_dwordx4 v[10:11], v[2:5], off offset:448
	v_mfma_f32_16x16x32_bf16 v[6:9], v[80:83], v[76:79], v[6:9]
	s_nop 0
	v_add_co_u32_e32 v2, vcc, 0x2000, v10
	s_nop 1
	v_addc_co_u32_e32 v3, vcc, 0, v11, vcc
	global_store_dwordx4 v[2:3], v[14:17], off
	global_store_dwordx4 v[2:3], v[24:27], off offset:64
	global_store_dwordx4 v[2:3], v[32:35], off offset:128
	global_store_dwordx4 v[2:3], v[40:43], off offset:192
	global_store_dwordx4 v[2:3], v[48:51], off offset:256
	global_store_dwordx4 v[2:3], v[56:59], off offset:320
	global_store_dwordx4 v[2:3], v[64:67], off offset:384
	global_store_dwordx4 v[2:3], v[6:9], off offset:448

.LBB0_332:
	s_or_b64 exec, exec, s[4:5]
	s_add_i32 s2, s24, 0xffffff80
	v_readlane_b32 s4, v254, 18
	s_add_i32 s4, s2, s4
	s_mul_i32 s5, s6, 0x1400
	v_readlane_b32 s8, v254, 1
	s_mul_hi_u32 s2, s6, 0x1400
	v_readlane_b32 s9, v254, 2
	s_add_u32 s8, s8, s5
	v_ashrrev_i32_e32 v7, 31, v6
	s_addc_u32 s9, s9, s2
	v_lshl_add_u64 v[2:3], v[6:7], 1, s[8:9]
	global_load_ushort v0, v[2:3], off offset:2048
	s_lshl_b64 s[8:9], s[6:7], 5
	v_readlane_b32 s10, v254, 11
	v_readlane_b32 s11, v254, 12
	s_add_u32 s8, s10, s8
	v_ashrrev_i32_e32 v8, 6, v6
	s_addc_u32 s9, s11, s9
	v_readlane_b32 s10, v253, 42
	v_lshl_add_u32 v80, v6, 2, 0
	v_ashrrev_i32_e32 v9, 31, v8
	v_readlane_b32 s11, v253, 43
	v_lshl_add_u64 v[2:3], v[8:9], 2, s[8:9]
	v_readlane_b32 s2, v253, 58
	s_ashr_i32 s5, s4, 31
	v_lshlrev_b64 v[14:15], 13, v[8:9]
	v_add_u32_e32 v10, s2, v8
	v_ashrrev_i32_e32 v11, 31, v10
	s_lshl_b64 s[4:5], s[4:5], 16
	v_lshl_add_u64 v[14:15], v[14:15], 0, s[4:5]
	v_and_b32_e32 v13, 63, v6
	v_lshlrev_b64 v[14:15], 2, v[14:15]
	v_lshl_add_u64 v[18:19], s[12:13], 0, v[14:15]
	v_and_b32_e32 v9, 0xffffffc0, v6
	s_mov_b32 s17, 0
	v_cmp_eq_u32_e64 s[4:5], 0, v13
	s_waitcnt vmcnt(0)
	v_lshlrev_b32_e32 v0, 16, v0
	ds_write_b32 v80, v0 offset:4096
	s_waitcnt lgkmcnt(0)
	s_barrier
	s_load_dwordx2 s[8:9], s[10:11], 0x90
	global_load_dword v81, v[2:3], off
	s_waitcnt lgkmcnt(0)
	v_lshl_add_u64 v[2:3], v[10:11], 2, s[8:9]
	global_load_dword v0, v[2:3], off
	s_load_dwordx2 s[8:9], s[10:11], 0x30
	s_waitcnt lgkmcnt(0)
	v_lshl_add_u64 v[16:17], s[8:9], 0, v[14:15]
	s_mov_b64 s[8:9], -1
	s_waitcnt vmcnt(0)
	v_mul_f32_e32 v0, 0x3fb8aa3b, v0
	v_exp_f32_e32 v0, v0
	s_nop 0
	v_mul_f32_e64 v0, v81, -v0
	v_mul_f32_e32 v0, 0x3fb8aa3b, v0
	v_exp_f32_e32 v12, v0
	v_lshlrev_b32_e32 v0, 1, v6
	v_and_b32_e32 v2, 0xfffffe00, v0
	v_lshlrev_b32_e32 v0, 3, v13
	v_add3_u32 v2, 0, v2, v0
	v_lshl_add_u64 v[14:15], v[16:17], 0, v[0:1]
	v_lshl_add_u64 v[16:17], v[18:19], 0, v[0:1]
	v_and_b32_e32 v0, 64, v243
	v_add_u32_e32 v18, 64, v0
	v_xor_b32_e32 v0, 32, v243
	v_cmp_lt_i32_e32 vcc, v0, v18
	v_xor_b32_e32 v19, 16, v243
	ds_read2st64_b64 v[2:5], v2 offset0:4 offset1:6
	v_cndmask_b32_e32 v0, v243, v0, vcc
	v_cmp_lt_i32_e32 vcc, v19, v18
	v_lshlrev_b32_e32 v0, 2, v0
	v_mov_b32_e32 v13, v12
	v_cndmask_b32_e32 v19, v243, v19, vcc
	v_lshlrev_b32_e32 v82, 2, v19
	v_xor_b32_e32 v19, 8, v243
	v_cmp_lt_i32_e32 vcc, v19, v18
	s_nop 1
	v_cndmask_b32_e32 v19, v243, v19, vcc
	v_lshlrev_b32_e32 v83, 2, v19
	v_xor_b32_e32 v19, 4, v243
	v_cmp_lt_i32_e32 vcc, v19, v18
	s_nop 1
	v_cndmask_b32_e32 v19, v243, v19, vcc
	v_lshlrev_b32_e32 v84, 2, v19
	v_xor_b32_e32 v19, 2, v243
	v_cmp_lt_i32_e32 vcc, v19, v18
	s_nop 1
	v_cndmask_b32_e32 v19, v243, v19, vcc
	v_lshlrev_b32_e32 v85, 2, v19
	v_xor_b32_e32 v19, 1, v243
	v_cmp_lt_i32_e32 vcc, v19, v18
	s_nop 1
	v_cndmask_b32_e32 v18, v243, v19, vcc
	v_lshlrev_b32_e32 v86, 2, v18
	s_branch .LBB0_334
	s_nop 0
	s_nop 0

.LBB0_579:
	v_lshl_add_u64 v[22:23], v[4:5], 0, s[4:5]
	ds_read_b128 v[6:9], v3
	ds_read_b128 v[10:13], v3 offset:16
	ds_read_b128 v[14:17], v3 offset:32
	ds_read_b128 v[18:21], v3 offset:48
	ds_read_b128 v[36:39], v3 offset:64
	ds_read_b128 v[40:43], v3 offset:80
	ds_read_b128 v[44:47], v3 offset:96
	ds_read_b128 v[48:51], v3 offset:112
	v_add_co_u32_e32 v84, vcc, s9, v22
	s_nop 1
	v_addc_co_u32_e32 v85, vcc, 0, v23, vcc
	global_load_dword v52, v[22:23], off
	global_load_dword v53, v[22:23], off offset:256
	global_load_dword v54, v[22:23], off offset:512
	global_load_dword v55, v[22:23], off offset:768
	global_load_dword v56, v[22:23], off offset:1024
	global_load_dword v57, v[22:23], off offset:1280
	global_load_dword v58, v[22:23], off offset:1536
	global_load_dword v59, v[22:23], off offset:1792
	global_load_dword v60, v[22:23], off offset:2048
	global_load_dword v61, v[22:23], off offset:2304
	global_load_dword v62, v[22:23], off offset:2560
	global_load_dword v63, v[22:23], off offset:2816
	global_load_dword v64, v[22:23], off offset:3072
	global_load_dword v65, v[22:23], off offset:3328
	global_load_dword v66, v[22:23], off offset:3584
	global_load_dword v67, v[22:23], off offset:3840
	global_load_dword v68, v[84:85], off
	global_load_dword v69, v[84:85], off offset:256
	global_load_dword v70, v[84:85], off offset:512
	global_load_dword v71, v[84:85], off offset:768
	global_load_dword v72, v[84:85], off offset:1024
	global_load_dword v73, v[84:85], off offset:1280
	global_load_dword v74, v[84:85], off offset:1536
	global_load_dword v75, v[84:85], off offset:1792
	global_load_dword v76, v[84:85], off offset:2048
	global_load_dword v77, v[84:85], off offset:2304
	global_load_dword v78, v[84:85], off offset:2560
	global_load_dword v79, v[84:85], off offset:2816
	global_load_dword v80, v[84:85], off offset:3072
	global_load_dword v81, v[84:85], off offset:3328
	global_load_dword v82, v[84:85], off offset:3584
	global_load_dword v83, v[84:85], off offset:3840
	v_add_u32_e32 v3, 0x80, v3
	s_add_u32 s4, s4, 0x2000
	s_addc_u32 s5, s5, 0
	s_cmpk_eq_i32 s4, 0x4000
	s_waitcnt vmcnt(0) lgkmcnt(0)
	v_fmac_f32_e32 v0, v6, v52
	v_fmac_f32_e32 v0, v7, v53
	v_fmac_f32_e32 v0, v8, v54
	v_fmac_f32_e32 v0, v9, v55
	v_fmac_f32_e32 v0, v10, v56
	v_fmac_f32_e32 v0, v11, v57
	v_fmac_f32_e32 v0, v12, v58
	v_fmac_f32_e32 v0, v13, v59
	v_fmac_f32_e32 v0, v14, v60
	v_fmac_f32_e32 v0, v15, v61
	v_fmac_f32_e32 v0, v16, v62
	v_fmac_f32_e32 v0, v17, v63
	v_fmac_f32_e32 v0, v18, v64
	v_fmac_f32_e32 v0, v19, v65
	v_fmac_f32_e32 v0, v20, v66
	v_fmac_f32_e32 v0, v21, v67
	v_fmac_f32_e32 v0, v36, v68
	v_fmac_f32_e32 v0, v37, v69
	v_fmac_f32_e32 v0, v38, v70
	v_fmac_f32_e32 v0, v39, v71
	v_fmac_f32_e32 v0, v40, v72
	v_fmac_f32_e32 v0, v41, v73
	v_fmac_f32_e32 v0, v42, v74
	v_fmac_f32_e32 v0, v43, v75
	v_fmac_f32_e32 v0, v44, v76
	v_fmac_f32_e32 v0, v45, v77
	v_fmac_f32_e32 v0, v46, v78
	v_fmac_f32_e32 v0, v47, v79
	v_fmac_f32_e32 v0, v48, v80
	v_fmac_f32_e32 v0, v49, v81
	v_fmac_f32_e32 v0, v50, v82
	v_fmac_f32_e32 v0, v51, v83
	s_cbranch_scc0 .LBB0_579
	v_readlane_b32 s4, v253, 42
	v_readlane_b32 s5, v253, 43
	s_load_dwordx2 s[4:5], s[4:5], 0x70
	v_add_u32_e32 v4, s18, v2
	v_ashrrev_i32_e32 v5, 31, v4
	v_readlane_b32 s22, v254, 3
	v_readlane_b32 s23, v254, 4
	s_waitcnt lgkmcnt(0)
	v_lshl_add_u64 v[4:5], v[4:5], 2, s[4:5]
	global_load_dword v4, v[4:5], off
	s_lshl_b64 s[4:5], s[12:13], 11
	s_add_u32 s4, s22, s4
	v_ashrrev_i32_e32 v3, 31, v2
	s_addc_u32 s5, s23, s5
	s_waitcnt vmcnt(0)
	v_mul_f32_e32 v0, v0, v4
	v_lshl_add_u64 v[4:5], v[2:3], 1, s[4:5]
	v_cvt_pk_bf16_f32 v0, v0, v1
	global_store_short v[4:5], v0, off

.LBB0_595:
	global_load_ushort v14, v[6:7], off
	v_add_u32_e32 v0, 0x200, v0
	v_lshl_add_u64 v[6:7], v[6:7], 0, s[34:35]
	s_waitcnt vmcnt(0)
	v_lshlrev_b32_e32 v18, 16, v14
	v_lshl_add_u64 v[14:15], v[12:13], 0, s[10:11]
	v_add_co_u32_e32 v16, vcc, 0x1000, v14
	global_load_dword v19, v[14:15], off
	s_nop 0
	v_addc_co_u32_e32 v17, vcc, 0, v15, vcc
	global_load_dword v20, v[16:17], off
	v_add_co_u32_e32 v14, vcc, 0x2000, v14
	s_nop 1
	v_addc_co_u32_e32 v15, vcc, 0, v15, vcc
	global_load_dword v21, v[14:15], off
	v_lshl_add_u64 v[14:15], v[4:5], 0, s[10:11]
	global_load_dword v22, v[14:15], off
	v_lshl_add_u64 v[14:15], v[10:11], 0, s[10:11]
	global_load_dword v16, v[14:15], off
	s_waitcnt vmcnt(0)
	v_fmac_f32_e32 v22, v19, v16
	v_add_co_u32_e32 v16, vcc, 0x1000, v14
	s_nop 1
	v_addc_co_u32_e32 v17, vcc, 0, v15, vcc
	global_load_dword v16, v[16:17], off
	s_waitcnt vmcnt(0)
	v_fmac_f32_e32 v22, v20, v16
	v_add_co_u32_e32 v16, vcc, s30, v14
	s_nop 1
	v_addc_co_u32_e32 v17, vcc, 0, v15, vcc
	v_add_co_u32_e32 v14, vcc, 0x3000, v14
	global_load_dword v16, v[16:17], off
	s_nop 0
	v_addc_co_u32_e32 v15, vcc, 0, v15, vcc
	global_load_dword v14, v[14:15], off
	s_waitcnt vmcnt(1)
	v_fmac_f32_e32 v22, v21, v16
	s_waitcnt vmcnt(0)
	v_fmac_f32_e32 v22, v14, v18
	v_mul_f32_e32 v14, 0xbfb8aa3b, v22
	v_exp_f32_e32 v14, v14
	s_nop 0
	v_add_f32_e32 v14, 1.0, v14
	v_rcp_f32_e32 v14, v14
	s_nop 0
	v_mul_f32_e32 v14, v22, v14
	v_cvt_pk_bf16_f32 v14, v14, v1
	global_store_short v[8:9], v14, off
	v_lshl_add_u64 v[14:15], v[2:3], 0, s[10:11]
	v_add_co_u32_e32 v16, vcc, 0x1a146000, v14
	s_add_u32 s10, s10, 0x800
	s_nop 0
	v_addc_co_u32_e32 v17, vcc, 0, v15, vcc
	global_store_dword v[16:17], v20, off
	v_add_co_u32_e32 v16, vcc, 0x1a147000, v14
	s_addc_u32 s11, s11, 0
	s_nop 0
	v_addc_co_u32_e32 v17, vcc, 0, v15, vcc
	v_add_co_u32_e32 v14, vcc, 0x1a148000, v14
	v_lshl_add_u64 v[8:9], v[8:9], 0, s[34:35]
	s_nop 0
	v_addc_co_u32_e32 v15, vcc, 0, v15, vcc
	v_cmp_lt_i32_e32 vcc, s31, v0
	s_or_b64 s[8:9], vcc, s[8:9]
	global_store_dword v[16:17], v21, off
	global_store_dword v[14:15], v18, off
	s_andn2_b64 exec, exec, s[8:9]
	s_cbranch_execnz .LBB0_595
	s_branch .LBB0_572
	s_nop 0
	s_nop 0
	s_nop 0
	s_nop 0
	s_nop 0
	s_nop 0
	s_nop 0
	s_nop 0
	s_nop 0
	s_nop 0
	s_nop 0
	s_nop 0
	s_nop 0
	s_nop 0
